# v16 + w_in_b transposes LDS staging skewed by one dword per 8-row block (transposed reads spread over all banks)
# baseline (speedup 1.0000x reference)
; #define LAS __attribute__((address_space(3)))
; template <bool REMAP = false>
; __device__ __forceinline__ void transpose_convert(LAS unsigned char* lds, const float* src, bf16_t* dst, int K, int N, int G, int bid) {
;     LAS float* tile = (LAS float*)lds;
;     const int tid = threadIdx.x, ntn = N / 64, ntiles = (K / 128) * ntn;
;     const int r0 = tid >> 4, c4 = tid & 15;
;     f32x4 v[4];
;     if (bid < ntiles) { const int k0 = (bid / ntn) * 128, n0 = (bid % ntn) * 64;
; #pragma unroll
;         for (int i = 0; i < 4; ++i) v[i] = __builtin_nontemporal_load((const f32x4*)(src + (size_t)(k0 + r0 + 32 * i) * N + n0 + c4 * 4)); }
;     for (int t = bid; t < ntiles; t += G) {
;         const int k0 = (t / ntn) * 128, n0 = (t % ntn) * 64;
;         asm volatile("s_waitcnt lgkmcnt(0)" ::: "memory"); __builtin_amdgcn_s_barrier(); asm volatile("" ::: "memory");
; #pragma unroll
;         for (int i = 0; i < 4; ++i) {
; #pragma unroll
;             for (int j = 0; j < 4; ++j) tile[(r0 + 32 * i) * 65 + c4 * 4 + j] = v[i][j]; }
;         asm volatile("s_waitcnt lgkmcnt(0)" ::: "memory"); __builtin_amdgcn_s_barrier(); asm volatile("" ::: "memory");
;         if (t + G < ntiles) { const int k1 = ((t + G) / ntn) * 128, n1 = ((t + G) % ntn) * 64;
; #pragma unroll
;             for (int i = 0; i < 4; ++i) v[i] = __builtin_nontemporal_load((const f32x4*)(src + (size_t)(k1 + r0 + 32 * i) * N + n1 + c4 * 4)); }
; #pragma unroll
;         for (int i = 0; i < 2; ++i) { const int id = tid + 512 * i, n = id >> 4, kc = id & 15;
;             float f[8];
; #pragma unroll
;             for (int j = 0; j < 8; ++j) f[j] = tile[(kc * 8 + j) * 65 + n];
.Lrk5_done:
	s_mul_i32 s4, s4, s100
	s_add_i32 s99, s5, s4
	s_add_i32 s100, s99, s100
	s_ashr_i32 s3, s99, 31
	s_lshr_b32 s3, s3, 25
	s_add_i32 s3, s99, s3
	s_and_b32 s3, s3, 0xffffff80
	s_sub_i32 s4, s99, s3
	s_lshl_b32 s4, s4, 6
	s_ashr_i32 s5, s4, 31
	s_lshl_b64 s[4:5], s[4:5], 2
	s_waitcnt vmcnt(0)
	v_or_b32_e32 v8, s3, v214
	s_add_u32 s4, s30, s4
	s_addc_u32 s5, s31, s5
	v_lshlrev_b32_e32 v18, 4, v20
	v_mov_b32_e32 v19, 0
	v_ashrrev_i32_e32 v9, 31, v8
	v_lshl_add_u64 v[10:11], s[4:5], 0, v[18:19]
	v_lshlrev_b64 v[0:1], 15, v[8:9]
	v_lshl_add_u64 v[12:13], v[10:11], 0, v[0:1]
	s_mov_b32 s3, 0x100000
	v_or_b32_e32 v8, 64, v8
	v_add_co_u32_e32 v14, vcc, s3, v12
	v_ashrrev_i32_e32 v9, 31, v8
	s_nop 0
	v_addc_co_u32_e32 v15, vcc, 0, v13, vcc
	v_lshlrev_b64 v[8:9], 15, v[8:9]
	s_mov_b32 s16, 0x300000
	v_lshl_add_u64 v[16:17], v[10:11], 0, v[8:9]
	v_add_co_u32_e32 v22, vcc, s16, v12
	global_load_dwordx4 v[0:3], v[12:13], off nt
	global_load_dwordx4 v[4:7], v[14:15], off nt
	v_addc_co_u32_e32 v23, vcc, 0, v13, vcc
	global_load_dwordx4 v[8:11], v[16:17], off nt
	global_load_dwordx4 v[12:15], v[22:23], off nt
	v_add_u32_e32 v21, 0x200, v164
	v_add_u32_e32 v22, 0, v18
	v_lshrrev_b32_e32 v21, 4, v21
	v_mul_u32_u24_e32 v23, 0x104, v214
	v_lshrrev_b32_e32 v249, 3, v214
	v_lshl_add_u32 v23, v249, 2, v23
	v_lshl_add_u32 v27, v21, 2, 0
	v_mul_u32_u24_e32 v28, 0x824, v20
	v_lshl_add_u32 v26, v214, 2, 0
	v_add_u32_e32 v22, v22, v23
	v_lshl_add_u64 v[16:17], s[30:31], 0, v[18:19]
	v_lshl_add_u64 v[18:19], s[40:41], 0, v[18:19]
	s_lshl_b32 s18, s99, 6
	s_movk_i32 s17, 64
	v_add_u32_e32 v23, 0x2090, v22
	v_add_u32_e32 v24, 0x2098, v22
	v_add_u32_e32 v25, 0x4120, v22
	v_add_u32_e32 v26, v26, v28
	v_add_u32_e32 v27, v27, v28
	v_add_u32_e32 v28, 0x4128, v22
	v_add_u32_e32 v29, 0x61b0, v22
	s_mov_b32 s19, s99
	s_branch .LBB0_420

; template <bool REMAP = false>
; __device__ __forceinline__ void transpose_convert(LAS unsigned char* lds, const float* src, bf16_t* dst, int K, int N, int G, int bid) {
;     ...
;         asm volatile("s_waitcnt lgkmcnt(0)" ::: "memory"); __builtin_amdgcn_s_barrier(); asm volatile("" ::: "memory");
; #pragma unroll
;         for (int i = 0; i < 4; ++i) {
; #pragma unroll
;             for (int j = 0; j < 4; ++j) tile[(r0 + 32 * i) * 65 + c4 * 4 + j] = v[i][j]; }
;         asm volatile("s_waitcnt lgkmcnt(0)" ::: "memory"); __builtin_amdgcn_s_barrier(); asm volatile("" ::: "memory");
.LBB0_420:
	s_nop 0
	v_add_u32_e32 v30, 0x61b8, v22
	s_waitcnt lgkmcnt(0)
	s_barrier
	s_waitcnt vmcnt(3)
	ds_write2_b32 v22, v0, v1 offset1:1
	ds_write2_b32 v22, v2, v3 offset0:2 offset1:3
	s_waitcnt vmcnt(2)
	ds_write2_b32 v23, v4, v5 offset1:1
	ds_write2_b32 v24, v6, v7 offset1:1
	s_waitcnt vmcnt(1)
	ds_write2_b32 v25, v8, v9 offset1:1
	ds_write2_b32 v28, v10, v11 offset1:1
	s_waitcnt vmcnt(0)
	ds_write2_b32 v29, v12, v13 offset1:1
	ds_write2_b32 v30, v14, v15 offset1:1
	s_waitcnt lgkmcnt(0)
	s_barrier
	s_add_i32 s22, s19, 1
	s_cmp_ge_i32 s22, s100
	s_cselect_b64 s[4:5], -1, 0
	s_cmp_lt_i32 s22, s100
	s_mov_b64 s[6:7], -1
	s_cbranch_scc1 .LBB0_422
	s_add_i32 s23, s18, s17
	s_mov_b64 s[6:7], 0
